# v25 per-XCD head-major attention queue + W_down GEMM consumes row tiles newest-first within each XCD block + V-fragment LDS prefetch depth 6 (3 extra slots in dead QK accumulator registers)
# speedup vs baseline: 1.0152x; 1.0008x over previous
.LBB0_280:
	s_add_u32 s2, s12, s56
	s_addc_u32 s24, s13, s57
	s_add_u32 s28, s2, 0x80000
	s_addc_u32 s29, s24, 0
	s_add_i32 s19, s22, s84
	s_mov_b32 m0, s19
	s_nop 0
	global_load_lds_dwordx4 v245, s[28:29]
	s_add_i32 s19, s22, s86
	s_mov_b32 m0, s19
	s_nop 0
	global_load_lds_dwordx4 v247, s[28:29]
	s_add_u32 s28, s16, s56
	s_addc_u32 s29, s17, s57
	s_add_u32 s50, s28, 0x40000
	s_addc_u32 s51, s29, 0
	s_lshl_b32 s19, s1, 1
	s_add_i32 s19, s19, s85
	s_mov_b32 m0, s19
	s_nop 0
	global_load_lds_dwordx4 v246, s[50:51]
	s_addk_i32 s19, 0x2000
	s_mov_b32 m0, s19
	s_nop 0
	global_load_lds_dwordx4 v248, s[50:51]
	v_add_f32_e32 v1, v96, v97
	v_add_f32_e32 v1, v98, v1
	v_add_f32_e32 v1, v99, v1
	s_lshl_b32 s18, s18, 1
	v_add_f32_e32 v1, v100, v1
	v_add_u32_e32 v221, s18, v251
	v_add_f32_e32 v1, v101, v1
	v_cvt_pk_bf16_f32 v172, v96, v97
	v_cvt_pk_bf16_f32 v173, v98, v99
	s_waitcnt lgkmcnt(7)
	v_mfma_f32_32x32x16_bf16 v[112:127], v[204:207], v[164:167], 0
	s_nop 0
	v_add_f32_e32 v1, v102, v1
	v_add_f32_e32 v1, v103, v1
	v_add_f32_e32 v1, v104, v1
	v_add_f32_e32 v1, v105, v1
	v_cvt_pk_bf16_f32 v174, v100, v101
	v_cvt_pk_bf16_f32 v175, v102, v103
	s_waitcnt lgkmcnt(6)
	v_mfma_f32_32x32x16_bf16 v[128:143], v[196:199], v[164:167], 0
	v_add_f32_e32 v1, v106, v1
	v_add_f32_e32 v1, v107, v1
	v_add_f32_e32 v1, v108, v1
	v_add_f32_e32 v1, v109, v1
	v_cvt_pk_bf16_f32 v168, v104, v105
	v_cvt_pk_bf16_f32 v169, v106, v107
	s_waitcnt lgkmcnt(5)
	v_mfma_f32_32x32x16_bf16 v[112:127], v[200:203], v[156:159], v[112:127]
	s_nop 0
	v_add_f32_e32 v1, v110, v1
	v_add_f32_e32 v1, v111, v1
	v_add_f32_e32 v1, v80, v1
	v_add_f32_e32 v1, v81, v1
	v_cvt_pk_bf16_f32 v170, v108, v109
	v_cvt_pk_bf16_f32 v171, v110, v111
	s_waitcnt lgkmcnt(4)
	v_mfma_f32_32x32x16_bf16 v[128:143], v[192:195], v[156:159], v[128:143]
	s_nop 0
	v_add_f32_e32 v1, v82, v1
	v_add_f32_e32 v1, v83, v1
	v_add_f32_e32 v1, v84, v1
	v_add_f32_e32 v1, v85, v1
	v_cvt_pk_bf16_f32 v160, v80, v81
	v_cvt_pk_bf16_f32 v161, v82, v83
	s_waitcnt lgkmcnt(3)
	v_mfma_f32_32x32x16_bf16 v[112:127], v[188:191], v[148:151], v[112:127]
	s_nop 0
	v_add_f32_e32 v1, v86, v1
	v_add_f32_e32 v1, v87, v1
	v_add_f32_e32 v1, v88, v1
	v_add_f32_e32 v1, v89, v1
	v_cvt_pk_bf16_f32 v162, v84, v85
	v_cvt_pk_bf16_f32 v163, v86, v87
	s_waitcnt lgkmcnt(2)
	v_mfma_f32_32x32x16_bf16 v[128:143], v[184:187], v[148:151], v[128:143]
	s_nop 0
	v_add_f32_e32 v1, v90, v1
	v_add_f32_e32 v1, v91, v1
	v_add_f32_e32 v1, v92, v1
	v_add_f32_e32 v1, v93, v1
	v_cvt_pk_bf16_f32 v152, v88, v89
	v_cvt_pk_bf16_f32 v153, v90, v91
	s_waitcnt lgkmcnt(1)
	v_mfma_f32_32x32x16_bf16 v[112:127], v[180:183], v[144:147], v[112:127]
	s_nop 0
	v_add_f32_e32 v1, v94, v1
	v_add_f32_e32 v1, v95, v1
	v_add_f32_e32 v1, 0, v1
	v_cvt_pk_bf16_f32 v154, v92, v93
	v_cvt_pk_bf16_f32 v155, v94, v95
	s_waitcnt lgkmcnt(0)
	v_mfma_f32_32x32x16_bf16 v[128:143], v[176:179], v[144:147], v[128:143]
	ds_read_b64_tr_b16 v[10:11], v221 offset:49152
	ds_read_b64_tr_b16 v[12:13], v221 offset:49664
	ds_read_b64_tr_b16 v[6:7], v221 offset:53248
	ds_read_b64_tr_b16 v[8:9], v221 offset:53760
	ds_read_b64_tr_b16 v[2:3], v221 offset:50176
	ds_read_b64_tr_b16 v[4:5], v221 offset:50688
	v_add_f32_e32 v219, v215, v218
	v_add_f32_e32 v84, v215, v219
	v_add_f32_e32 v85, v215, v84
	v_add_f32_e32 v88, v250, v85
	v_add_f32_e32 v89, v215, v88
	v_add_f32_e32 v82, v216, v218
	v_pk_add_f32 v[100:101], v[88:89], v[116:117]
	v_add_f32_e32 v88, v215, v89
	v_add_f32_e32 v83, v215, v82
	v_add_f32_e32 v89, v215, v88
	v_add_f32_e32 v86, v215, v83
	v_add_f32_e32 v92, v250, v89
	v_add_f32_e32 v87, v215, v86
	v_add_f32_e32 v93, v215, v92
	v_pk_add_f32 v[14:15], v[82:83], v[128:129]
	v_pk_add_f32 v[82:83], v[86:87], v[130:131]
	v_add_f32_e32 v86, v250, v87
	v_pk_add_f32 v[104:105], v[92:93], v[120:121]
	v_add_f32_e32 v92, v215, v93
	v_add_f32_e32 v87, v215, v86
	v_add_f32_e32 v93, v215, v92
	v_add_f32_e32 v90, v215, v87
	v_add_f32_e32 v96, v250, v93
	v_add_f32_e32 v91, v215, v90
	v_add_f32_e32 v97, v215, v96
	v_pk_add_f32 v[98:99], v[84:85], v[114:115]
	v_pk_add_f32 v[84:85], v[86:87], v[132:133]
	v_pk_add_f32 v[86:87], v[90:91], v[134:135]
	ds_read_b64_tr_b16 v[132:133], v221 offset:54272
	ds_read_b64_tr_b16 v[134:135], v221 offset:54784
	v_add_f32_e32 v90, v250, v91
	v_pk_add_f32 v[108:109], v[96:97], v[124:125]
	v_add_f32_e32 v96, v215, v97
	v_pk_add_f32 v[80:81], v[218:219], v[112:113]
	v_add_f32_e32 v91, v215, v90
	v_add_f32_e32 v97, v215, v96
	v_add_f32_e32 v94, v215, v91
	v_pk_add_f32 v[110:111], v[96:97], v[126:127]
	v_max_f32_e32 v96, v80, v81
	v_pk_add_f32 v[102:103], v[88:89], v[118:119]
	v_add_f32_e32 v95, v215, v94
	v_max3_f32 v97, v98, v99, v15
	v_max3_f32 v96, v96, v14, v82
	v_pk_add_f32 v[88:89], v[90:91], v[136:137]
	v_pk_add_f32 v[90:91], v[94:95], v[138:139]
	ds_read_b64_tr_b16 v[136:137], v221 offset:51200
	ds_read_b64_tr_b16 v[138:139], v221 offset:51712
	v_add_f32_e32 v94, v250, v95
	v_max3_f32 v96, v96, v83, v100
	v_max3_f32 v97, v97, v102, v103
	v_pk_add_f32 v[106:107], v[92:93], v[122:123]
	v_add_f32_e32 v95, v215, v94
	v_max3_f32 v96, v96, v101, v84
	v_max3_f32 v97, v97, v86, v87
	v_pk_add_f32 v[92:93], v[94:95], v[140:141]
	v_add_f32_e32 v94, v215, v95
	v_max3_f32 v96, v96, v85, v104
	v_max3_f32 v97, v97, v106, v107
	v_add_f32_e32 v95, v215, v94
	v_max3_f32 v96, v96, v105, v88
	v_max3_f32 v97, v97, v90, v91
	v_pk_add_f32 v[94:95], v[94:95], v[142:143]
	ds_read_b64_tr_b16 v[140:141], v221 offset:55296
	ds_read_b64_tr_b16 v[142:143], v221 offset:55808
	v_max3_f32 v96, v96, v89, v108
	v_max3_f32 v97, v97, v110, v111
	v_max3_f32 v96, v96, v109, v92
	v_max3_f32 v97, v97, v94, v95
	v_max3_f32 v96, v96, v93, v97
	v_mov_b32_e32 v97, v96
	s_nop 1
	v_permlane32_swap_b32_e32 v96, v97
	v_max_f32_e32 v97, v97, v97
	v_max_f32_e32 v96, v96, v96
	v_max_f32_e32 v96, v96, v97
	v_cmp_lt_f32_e32 vcc, s20, v96
	s_cmp_lg_u64 vcc, 0
	v_add_f32_e32 v1, v254, v1
	s_cselect_b64 s[58:59], -1, 0
	s_cbranch_vccnz .LBB0_288
.LBB0_281:
	s_waitcnt lgkmcnt(10)
	v_mfma_f32_32x32x16_bf16 v[64:79], v[172:175], v[10:13], v[64:79]
	v_exp_f32_e32 v96, v80
	v_exp_f32_e32 v97, v81
	ds_read_b64_tr_b16 v[116:117], v221 offset:52224
	ds_read_b64_tr_b16 v[118:119], v221 offset:52736
	s_waitcnt lgkmcnt(10)
	v_mfma_f32_32x32x16_bf16 v[48:63], v[172:175], v[6:9], v[48:63]
	v_exp_f32_e32 v98, v98
	v_exp_f32_e32 v99, v99
	v_add_u32_e32 v80, s1, v249
	ds_read_b64_tr_b16 v[120:121], v221 offset:56320
	ds_read_b64_tr_b16 v[122:123], v221 offset:56832
	ds_read_b128 v[112:115], v80
	ds_read_b128 v[128:131], v80 offset:512
	s_waitcnt lgkmcnt(12)
	v_mfma_f32_32x32x16_bf16 v[64:79], v[168:171], v[2:5], v[64:79]
	v_exp_f32_e32 v100, v100
	v_exp_f32_e32 v101, v101
	ds_read_b64_tr_b16 v[124:125], v221 offset:57344
	ds_read_b64_tr_b16 v[126:127], v221 offset:57856
	ds_read_b128 v[184:187], v80 offset:2048
	ds_read_b128 v[180:183], v80 offset:2560
	s_waitcnt lgkmcnt(14)
	v_mfma_f32_32x32x16_bf16 v[48:63], v[168:171], v[132:135], v[48:63]
	v_exp_f32_e32 v102, v102
	v_exp_f32_e32 v103, v103
	ds_read_b64_tr_b16 v[132:133], v221 offset:61440
	ds_read_b64_tr_b16 v[134:135], v221 offset:61952
	ds_read_b128 v[176:179], v80 offset:4096
	ds_read_b128 v[10:13], v80 offset:4608
	s_waitcnt lgkmcnt(15)
	v_mfma_f32_32x32x16_bf16 v[64:79], v[160:163], v[136:139], v[64:79]
	v_exp_f32_e32 v104, v104
	v_exp_f32_e32 v105, v105
	ds_read_b64_tr_b16 v[136:137], v221 offset:58368
	ds_read_b64_tr_b16 v[138:139], v221 offset:58880
	ds_read_b128 v[6:9], v80 offset:6144
	ds_read_b128 v[2:5], v80 offset:6656
	s_waitcnt lgkmcnt(15)
	v_mfma_f32_32x32x16_bf16 v[48:63], v[160:163], v[140:143], v[48:63]
	v_exp_f32_e32 v106, v106
	v_exp_f32_e32 v107, v107
	ds_read_b64_tr_b16 v[140:141], v221 offset:62464
	ds_read_b64_tr_b16 v[142:143], v221 offset:62976
	s_waitcnt lgkmcnt(15)
	v_mfma_f32_32x32x16_bf16 v[64:79], v[152:155], v[116:119], v[64:79]
	v_exp_f32_e32 v108, v108
	v_exp_f32_e32 v109, v109
	ds_read_b64_tr_b16 v[116:117], v221 offset:59392
	ds_read_b64_tr_b16 v[118:119], v221 offset:59904
	s_waitcnt lgkmcnt(15)
	v_mfma_f32_32x32x16_bf16 v[48:63], v[152:155], v[120:123], v[48:63]
	v_exp_f32_e32 v110, v110
	v_exp_f32_e32 v111, v111
	ds_read_b64_tr_b16 v[120:121], v221 offset:63488
	ds_read_b64_tr_b16 v[122:123], v221 offset:64000
	s_waitcnt lgkmcnt(15)
	v_mfma_f32_32x32x16_bf16 v[32:47], v[172:175], v[124:127], v[32:47]
	v_exp_f32_e32 v80, v14
	v_exp_f32_e32 v81, v15
	ds_read_b64_tr_b16 v[124:125], v221 offset:60416
	ds_read_b64_tr_b16 v[126:127], v221 offset:60928
	s_waitcnt lgkmcnt(14)
	v_mfma_f32_32x32x16_bf16 v[16:31], v[172:175], v[132:135], v[16:31]
	v_exp_f32_e32 v82, v82
	v_exp_f32_e32 v83, v83
	ds_read_b64_tr_b16 v[132:133], v221 offset:64512
	ds_read_b64_tr_b16 v[134:135], v221 offset:65024
	s_waitcnt lgkmcnt(12)
	v_mfma_f32_32x32x16_bf16 v[32:47], v[168:171], v[136:139], v[32:47]
	v_exp_f32_e32 v84, v84
	v_exp_f32_e32 v85, v85
	s_waitcnt lgkmcnt(8)
	v_mfma_f32_32x32x16_bf16 v[16:31], v[168:171], v[140:143], v[16:31]
	v_exp_f32_e32 v86, v86
	v_exp_f32_e32 v87, v87
	s_waitcnt lgkmcnt(6)
	v_mfma_f32_32x32x16_bf16 v[32:47], v[160:163], v[116:119], v[32:47]
	v_exp_f32_e32 v88, v88
	v_exp_f32_e32 v89, v89
	s_waitcnt lgkmcnt(4)
	v_mfma_f32_32x32x16_bf16 v[16:31], v[160:163], v[120:123], v[16:31]
	v_exp_f32_e32 v90, v90
	v_exp_f32_e32 v91, v91
	s_waitcnt lgkmcnt(2)
	v_mfma_f32_32x32x16_bf16 v[32:47], v[152:155], v[124:127], v[32:47]
	v_exp_f32_e32 v92, v92
	v_exp_f32_e32 v93, v93
	s_waitcnt lgkmcnt(0)
	v_mfma_f32_32x32x16_bf16 v[16:31], v[152:155], v[132:135], v[16:31]
	v_exp_f32_e32 v94, v94
	v_exp_f32_e32 v95, v95
	s_waitcnt vmcnt(4) lgkmcnt(0)
	s_barrier
	s_andn2_b64 vcc, exec, s[58:59]
	s_cbranch_vccnz .LBB0_283
	s_waitcnt lgkmcnt(0)
	ds_read_b128 v[116:119], v209 offset:96
	ds_read_b128 v[120:123], v209 offset:64
	ds_read_b128 v[124:127], v209 offset:32
	ds_read_b128 v[132:135], v209
	s_waitcnt lgkmcnt(3)
	v_pk_mul_f32 v[78:79], v[78:79], v[118:119]
	s_waitcnt lgkmcnt(2)
	v_pk_mul_f32 v[74:75], v[74:75], v[122:123]
	s_waitcnt lgkmcnt(1)
	v_pk_mul_f32 v[70:71], v[70:71], v[126:127]
	s_waitcnt lgkmcnt(0)
	v_pk_mul_f32 v[66:67], v[66:67], v[134:135]
	v_pk_mul_f32 v[76:77], v[76:77], v[116:117]
	v_pk_mul_f32 v[72:73], v[72:73], v[120:121]
	v_pk_mul_f32 v[68:69], v[68:69], v[124:125]
	v_pk_mul_f32 v[64:65], v[64:65], v[132:133]
	v_pk_mul_f32 v[62:63], v[62:63], v[118:119]
	v_pk_mul_f32 v[58:59], v[58:59], v[122:123]
	v_pk_mul_f32 v[54:55], v[54:55], v[126:127]
	v_pk_mul_f32 v[50:51], v[50:51], v[134:135]
	v_pk_mul_f32 v[60:61], v[60:61], v[116:117]
	v_pk_mul_f32 v[56:57], v[56:57], v[120:121]
	v_pk_mul_f32 v[52:53], v[52:53], v[124:125]
	v_pk_mul_f32 v[48:49], v[48:49], v[132:133]
	v_pk_mul_f32 v[46:47], v[46:47], v[118:119]
	v_pk_mul_f32 v[42:43], v[42:43], v[122:123]
	v_pk_mul_f32 v[38:39], v[38:39], v[126:127]
	v_pk_mul_f32 v[34:35], v[34:35], v[134:135]
	v_pk_mul_f32 v[44:45], v[44:45], v[116:117]
	v_pk_mul_f32 v[40:41], v[40:41], v[120:121]
	v_pk_mul_f32 v[36:37], v[36:37], v[124:125]
	v_pk_mul_f32 v[32:33], v[32:33], v[132:133]
	v_pk_mul_f32 v[30:31], v[30:31], v[118:119]
	v_pk_mul_f32 v[26:27], v[26:27], v[122:123]
	v_pk_mul_f32 v[22:23], v[22:23], v[126:127]
	v_pk_mul_f32 v[18:19], v[18:19], v[134:135]
	v_pk_mul_f32 v[28:29], v[28:29], v[116:117]
	v_pk_mul_f32 v[24:25], v[24:25], v[120:121]
	v_pk_mul_f32 v[20:21], v[20:21], v[124:125]
	v_pk_mul_f32 v[16:17], v[16:17], v[132:133]
.LBB0_283:
	v_subrev_u32_e32 v14, 64, v223
	v_cvt_f32_i32_e32 v14, v14
	s_add_i32 s18, s1, 0x2000
	s_cmpk_lg_i32 s1, 0x4000
	s_cselect_b32 s19, s18, 0
	v_fma_f32 v188, v215, v14, -v252
	s_add_u32 s50, s2, 0xa0000
	s_addc_u32 s51, s24, 0
	s_add_i32 s2, s1, s84
	s_mov_b32 m0, s2
	s_nop 0
	global_load_lds_dwordx4 v245, s[50:51]
	s_add_i32 s2, s1, s86
	s_add_u32 s28, s28, 0x60000
	s_mov_b32 m0, s2
	s_nop 0
	global_load_lds_dwordx4 v247, s[50:51]
	s_addc_u32 s29, s29, 0
	s_lshl_b32 s2, s19, 1
	s_add_i32 s2, s2, s85
	s_mov_b32 m0, s2
	s_nop 0
	global_load_lds_dwordx4 v246, s[28:29]
	s_addk_i32 s2, 0x2000
	s_mov_b32 m0, s2
	s_nop 0
	global_load_lds_dwordx4 v248, s[28:29]
	v_add_f32_e32 v14, v96, v97
	v_add_f32_e32 v14, v98, v14
	v_add_f32_e32 v14, v99, v14
	s_lshl_b32 s2, s22, 1
	v_add_f32_e32 v14, v100, v14
	v_add_u32_e32 v218, s2, v251
	v_add_f32_e32 v14, v101, v14
	v_cvt_pk_bf16_f32 v172, v96, v97
	v_cvt_pk_bf16_f32 v173, v98, v99
	v_mfma_f32_32x32x16_bf16 v[112:127], v[112:115], v[164:167], 0
	s_nop 0
	v_add_f32_e32 v14, v102, v14
	v_add_f32_e32 v14, v103, v14
	v_add_f32_e32 v14, v104, v14
	v_add_f32_e32 v14, v105, v14
	v_cvt_pk_bf16_f32 v174, v100, v101
	v_cvt_pk_bf16_f32 v175, v102, v103
	v_mfma_f32_32x32x16_bf16 v[128:143], v[128:131], v[164:167], 0
	v_add_f32_e32 v14, v106, v14
	v_add_f32_e32 v14, v107, v14
	v_add_f32_e32 v14, v108, v14
	v_add_f32_e32 v14, v109, v14
	v_cvt_pk_bf16_f32 v168, v104, v105
	v_cvt_pk_bf16_f32 v169, v106, v107
	v_mfma_f32_32x32x16_bf16 v[112:127], v[184:187], v[156:159], v[112:127]
	s_nop 0
	v_add_f32_e32 v14, v110, v14
	v_add_f32_e32 v14, v111, v14
	v_add_f32_e32 v14, v80, v14
	v_add_f32_e32 v14, v81, v14
	v_cvt_pk_bf16_f32 v170, v108, v109
	v_cvt_pk_bf16_f32 v171, v110, v111
	v_mfma_f32_32x32x16_bf16 v[128:143], v[180:183], v[156:159], v[128:143]
	s_nop 0
	v_add_f32_e32 v14, v82, v14
	v_add_f32_e32 v14, v83, v14
	v_add_f32_e32 v14, v84, v14
	v_add_f32_e32 v14, v85, v14
	v_cvt_pk_bf16_f32 v160, v80, v81
	v_cvt_pk_bf16_f32 v161, v82, v83
	v_mfma_f32_32x32x16_bf16 v[112:127], v[176:179], v[148:151], v[112:127]
	v_mfma_f32_32x32x16_bf16 v[128:143], v[10:13], v[148:151], v[128:143]
	v_add_f32_e32 v10, v86, v14
	v_add_f32_e32 v10, v87, v10
	v_add_f32_e32 v10, v88, v10
	v_add_f32_e32 v10, v89, v10
	v_cvt_pk_bf16_f32 v162, v84, v85
	v_cvt_pk_bf16_f32 v163, v86, v87
	v_mfma_f32_32x32x16_bf16 v[112:127], v[6:9], v[144:147], v[112:127]
	v_add_f32_e32 v6, v90, v10
	v_add_f32_e32 v6, v91, v6
	v_add_f32_e32 v6, v92, v6
	v_add_f32_e32 v6, v93, v6
	v_cvt_pk_bf16_f32 v152, v88, v89
	v_cvt_pk_bf16_f32 v153, v90, v91
	v_mfma_f32_32x32x16_bf16 v[128:143], v[2:5], v[144:147], v[128:143]
	v_add_f32_e32 v2, v94, v6
	v_add_f32_e32 v2, v95, v2
	v_add_f32_e32 v176, 0, v2
	v_cvt_pk_bf16_f32 v154, v92, v93
	v_cvt_pk_bf16_f32 v155, v94, v95
	ds_read_b64_tr_b16 v[10:11], v218 offset:49152
	ds_read_b64_tr_b16 v[12:13], v218 offset:49664
	ds_read_b64_tr_b16 v[6:7], v218 offset:53248
	ds_read_b64_tr_b16 v[8:9], v218 offset:53760
	ds_read_b64_tr_b16 v[2:3], v218 offset:50176
	ds_read_b64_tr_b16 v[4:5], v218 offset:50688
	v_add_f32_e32 v189, v215, v188
	v_add_f32_e32 v84, v215, v189
	v_add_f32_e32 v85, v215, v84
	v_add_f32_e32 v88, v250, v85
	v_add_f32_e32 v89, v215, v88
	v_add_f32_e32 v82, v216, v188
	v_pk_add_f32 v[100:101], v[88:89], v[116:117]
	v_add_f32_e32 v88, v215, v89
	v_add_f32_e32 v83, v215, v82
	v_add_f32_e32 v89, v215, v88
	v_add_f32_e32 v86, v215, v83
	v_add_f32_e32 v92, v250, v89
	v_add_f32_e32 v87, v215, v86
	v_add_f32_e32 v93, v215, v92
	v_pk_add_f32 v[14:15], v[82:83], v[128:129]
	v_pk_add_f32 v[82:83], v[86:87], v[130:131]
	v_add_f32_e32 v86, v250, v87
	v_pk_add_f32 v[104:105], v[92:93], v[120:121]
	v_add_f32_e32 v92, v215, v93
	v_add_f32_e32 v87, v215, v86
	v_add_f32_e32 v93, v215, v92
	v_add_f32_e32 v90, v215, v87
	v_add_f32_e32 v96, v250, v93
	v_add_f32_e32 v91, v215, v90
	v_add_f32_e32 v97, v215, v96
	v_pk_add_f32 v[98:99], v[84:85], v[114:115]
	v_pk_add_f32 v[84:85], v[86:87], v[132:133]
	v_pk_add_f32 v[86:87], v[90:91], v[134:135]
	ds_read_b64_tr_b16 v[132:133], v218 offset:54272
	ds_read_b64_tr_b16 v[134:135], v218 offset:54784
	v_add_f32_e32 v90, v250, v91
	v_pk_add_f32 v[108:109], v[96:97], v[124:125]
	v_add_f32_e32 v96, v215, v97
	v_pk_add_f32 v[80:81], v[188:189], v[112:113]
	v_add_f32_e32 v91, v215, v90
	v_add_f32_e32 v97, v215, v96
	v_add_f32_e32 v94, v215, v91
	v_pk_add_f32 v[110:111], v[96:97], v[126:127]
	v_max_f32_e32 v96, v80, v81
	v_pk_add_f32 v[102:103], v[88:89], v[118:119]
	v_add_f32_e32 v95, v215, v94
	v_max3_f32 v97, v98, v99, v15
	v_max3_f32 v96, v96, v14, v82
	v_pk_add_f32 v[88:89], v[90:91], v[136:137]
	v_pk_add_f32 v[90:91], v[94:95], v[138:139]
	ds_read_b64_tr_b16 v[136:137], v218 offset:51200
	ds_read_b64_tr_b16 v[138:139], v218 offset:51712
	v_add_f32_e32 v94, v250, v95
	v_max3_f32 v96, v96, v83, v100
	v_max3_f32 v97, v97, v102, v103
	v_pk_add_f32 v[106:107], v[92:93], v[122:123]
	v_add_f32_e32 v95, v215, v94
	v_max3_f32 v96, v96, v101, v84
	v_max3_f32 v97, v97, v86, v87
	v_pk_add_f32 v[92:93], v[94:95], v[140:141]
	v_add_f32_e32 v94, v215, v95
	v_max3_f32 v96, v96, v85, v104
	v_max3_f32 v97, v97, v106, v107
	v_add_f32_e32 v95, v215, v94
	v_max3_f32 v96, v96, v105, v88
	v_max3_f32 v97, v97, v90, v91
	v_pk_add_f32 v[94:95], v[94:95], v[142:143]
	ds_read_b64_tr_b16 v[140:141], v218 offset:55296
	ds_read_b64_tr_b16 v[142:143], v218 offset:55808
	v_max3_f32 v96, v96, v89, v108
	v_max3_f32 v97, v97, v110, v111
	v_max3_f32 v96, v96, v109, v92
	v_max3_f32 v97, v97, v94, v95
	v_add_f32_e32 v254, v1, v176
	v_max3_f32 v1, v96, v93, v97
	v_mov_b32_e32 v96, v1
	s_nop 1
	v_permlane32_swap_b32_e32 v1, v96
	v_max_f32_e32 v96, v96, v96
	v_max_f32_e32 v1, v1, v1
	v_max_f32_e32 v1, v1, v96
	v_cmp_lt_f32_e32 vcc, s20, v1
	s_cmp_lg_u64 vcc, 0
	s_cselect_b64 s[58:59], -1, 0
	s_cbranch_vccnz .LBB0_291
.LBB0_284:
	s_waitcnt lgkmcnt(10)
	v_mfma_f32_32x32x16_bf16 v[64:79], v[172:175], v[10:13], v[64:79]
	v_exp_f32_e32 v96, v80
	v_exp_f32_e32 v97, v81
	ds_read_b64_tr_b16 v[10:11], v218 offset:52224
	ds_read_b64_tr_b16 v[12:13], v218 offset:52736
	s_waitcnt lgkmcnt(10)
	v_mfma_f32_32x32x16_bf16 v[48:63], v[172:175], v[6:9], v[48:63]
	v_exp_f32_e32 v98, v98
	v_exp_f32_e32 v99, v99
	v_add_u32_e32 v1, s19, v249
	ds_read_b64_tr_b16 v[6:7], v218 offset:56320
	ds_read_b64_tr_b16 v[8:9], v218 offset:56832
	ds_read_b128 v[204:207], v1
	ds_read_b128 v[196:199], v1 offset:512
	s_waitcnt lgkmcnt(12)
	v_mfma_f32_32x32x16_bf16 v[64:79], v[168:171], v[2:5], v[64:79]
	v_exp_f32_e32 v100, v100
	v_exp_f32_e32 v101, v101
	ds_read_b64_tr_b16 v[2:3], v218 offset:57344
	ds_read_b64_tr_b16 v[4:5], v218 offset:57856
	ds_read_b128 v[200:203], v1 offset:2048
	ds_read_b128 v[192:195], v1 offset:2560
	s_waitcnt lgkmcnt(14)
	v_mfma_f32_32x32x16_bf16 v[48:63], v[168:171], v[132:135], v[48:63]
	v_exp_f32_e32 v102, v102
	v_exp_f32_e32 v103, v103
	ds_read_b64_tr_b16 v[132:133], v218 offset:61440
	ds_read_b64_tr_b16 v[134:135], v218 offset:61952
	ds_read_b128 v[188:191], v1 offset:4096
	ds_read_b128 v[184:187], v1 offset:4608
	s_waitcnt lgkmcnt(15)
	v_mfma_f32_32x32x16_bf16 v[64:79], v[160:163], v[136:139], v[64:79]
	v_exp_f32_e32 v104, v104
	v_exp_f32_e32 v105, v105
	ds_read_b64_tr_b16 v[136:137], v218 offset:58368
	ds_read_b64_tr_b16 v[138:139], v218 offset:58880
	ds_read_b128 v[180:183], v1 offset:6144
	ds_read_b128 v[176:179], v1 offset:6656
	s_waitcnt lgkmcnt(15)
	v_mfma_f32_32x32x16_bf16 v[48:63], v[160:163], v[140:143], v[48:63]
	v_exp_f32_e32 v106, v106
	v_exp_f32_e32 v107, v107
	ds_read_b64_tr_b16 v[140:141], v218 offset:62464
	ds_read_b64_tr_b16 v[142:143], v218 offset:62976
	s_waitcnt lgkmcnt(15)
	v_mfma_f32_32x32x16_bf16 v[64:79], v[152:155], v[10:13], v[64:79]
	v_exp_f32_e32 v108, v108
	v_exp_f32_e32 v109, v109
	ds_read_b64_tr_b16 v[10:11], v218 offset:59392
	ds_read_b64_tr_b16 v[12:13], v218 offset:59904
	s_waitcnt lgkmcnt(15)
	v_mfma_f32_32x32x16_bf16 v[48:63], v[152:155], v[6:9], v[48:63]
	v_exp_f32_e32 v110, v110
	v_exp_f32_e32 v111, v111
	ds_read_b64_tr_b16 v[6:7], v218 offset:63488
	ds_read_b64_tr_b16 v[8:9], v218 offset:64000
	s_waitcnt lgkmcnt(15)
	v_mfma_f32_32x32x16_bf16 v[32:47], v[172:175], v[2:5], v[32:47]
	v_exp_f32_e32 v80, v14
	v_exp_f32_e32 v81, v15
	ds_read_b64_tr_b16 v[2:3], v218 offset:60416
	ds_read_b64_tr_b16 v[4:5], v218 offset:60928
	s_waitcnt lgkmcnt(14)
	v_mfma_f32_32x32x16_bf16 v[16:31], v[172:175], v[132:135], v[16:31]
	v_exp_f32_e32 v82, v82
	v_exp_f32_e32 v83, v83
	ds_read_b64_tr_b16 v[132:133], v218 offset:64512
	ds_read_b64_tr_b16 v[134:135], v218 offset:65024
	s_waitcnt lgkmcnt(12)
	v_mfma_f32_32x32x16_bf16 v[32:47], v[168:171], v[136:139], v[32:47]
	v_exp_f32_e32 v84, v84
	v_exp_f32_e32 v85, v85
	s_waitcnt lgkmcnt(8)
	v_mfma_f32_32x32x16_bf16 v[16:31], v[168:171], v[140:143], v[16:31]
	v_exp_f32_e32 v86, v86
	v_exp_f32_e32 v87, v87
	s_waitcnt lgkmcnt(6)
	v_mfma_f32_32x32x16_bf16 v[32:47], v[160:163], v[10:13], v[32:47]
	v_exp_f32_e32 v88, v88
	v_exp_f32_e32 v89, v89
	s_waitcnt lgkmcnt(4)
	v_mfma_f32_32x32x16_bf16 v[16:31], v[160:163], v[6:9], v[16:31]
	v_exp_f32_e32 v90, v90
	v_exp_f32_e32 v91, v91
	s_waitcnt lgkmcnt(2)
	v_mfma_f32_32x32x16_bf16 v[32:47], v[152:155], v[2:5], v[32:47]
	v_exp_f32_e32 v92, v92
	v_exp_f32_e32 v93, v93
	s_waitcnt lgkmcnt(0)
	v_mfma_f32_32x32x16_bf16 v[16:31], v[152:155], v[132:135], v[16:31]
	v_exp_f32_e32 v94, v94
	v_exp_f32_e32 v95, v95
	s_waitcnt vmcnt(4) lgkmcnt(0)
	s_barrier
	s_andn2_b64 vcc, exec, s[58:59]
	s_cbranch_vccnz .LBB0_286
	s_waitcnt lgkmcnt(0)
	ds_read_b128 v[2:5], v209 offset:96
	ds_read_b128 v[6:9], v209 offset:64
	ds_read_b128 v[10:13], v209 offset:32
	ds_read_b128 v[112:115], v209
	s_waitcnt lgkmcnt(3)
	v_pk_mul_f32 v[78:79], v[78:79], v[4:5]
	s_waitcnt lgkmcnt(2)
	v_pk_mul_f32 v[74:75], v[74:75], v[8:9]
	s_waitcnt lgkmcnt(1)
	v_pk_mul_f32 v[70:71], v[70:71], v[12:13]
	s_waitcnt lgkmcnt(0)
	v_pk_mul_f32 v[66:67], v[66:67], v[114:115]
	v_pk_mul_f32 v[76:77], v[76:77], v[2:3]
	v_pk_mul_f32 v[72:73], v[72:73], v[6:7]
	v_pk_mul_f32 v[68:69], v[68:69], v[10:11]
	v_pk_mul_f32 v[64:65], v[64:65], v[112:113]
	v_pk_mul_f32 v[62:63], v[62:63], v[4:5]
	v_pk_mul_f32 v[58:59], v[58:59], v[8:9]
	v_pk_mul_f32 v[54:55], v[54:55], v[12:13]
	v_pk_mul_f32 v[50:51], v[50:51], v[114:115]
	v_pk_mul_f32 v[60:61], v[60:61], v[2:3]
	v_pk_mul_f32 v[56:57], v[56:57], v[6:7]
	v_pk_mul_f32 v[52:53], v[52:53], v[10:11]
	v_pk_mul_f32 v[48:49], v[48:49], v[112:113]
	v_pk_mul_f32 v[46:47], v[46:47], v[4:5]
	v_pk_mul_f32 v[42:43], v[42:43], v[8:9]
	v_pk_mul_f32 v[38:39], v[38:39], v[12:13]
	v_pk_mul_f32 v[34:35], v[34:35], v[114:115]
	v_pk_mul_f32 v[44:45], v[44:45], v[2:3]
	v_pk_mul_f32 v[40:41], v[40:41], v[6:7]
	v_pk_mul_f32 v[36:37], v[36:37], v[10:11]
	v_pk_mul_f32 v[32:33], v[32:33], v[112:113]
	v_pk_mul_f32 v[30:31], v[30:31], v[4:5]
	v_pk_mul_f32 v[26:27], v[26:27], v[8:9]
	v_pk_mul_f32 v[22:23], v[22:23], v[12:13]
	v_pk_mul_f32 v[18:19], v[18:19], v[114:115]
	v_pk_mul_f32 v[28:29], v[28:29], v[2:3]
	v_pk_mul_f32 v[24:25], v[24:25], v[6:7]
	v_pk_mul_f32 v[20:21], v[20:21], v[10:11]
	v_pk_mul_f32 v[16:17], v[16:17], v[112:113]

; #define PG8_STAGE(bufoff, gbase, voff) do { _Pragma("unroll") for (int _i = 0; _i < 2; ++_i) \
;         pg8_glds((const void*)(gbase), (voff)[_i], (unsigned)__builtin_amdgcn_readfirstlane((int)(lds_u + (unsigned)(bufoff) + ldsw + (unsigned)(_i * 8192)))); } while (0)
; #define PG8_WAIT_V(n) asm volatile("s_waitcnt vmcnt(" #n ")" ::: "memory")
; #define PG8_BAR __builtin_amdgcn_s_barrier()
;     __host__ __device__ bool next(int i, Unit& u) const {
;         const long L = (long)i * G + c; if (L >= nwg) return false;
;         int wgid = (int)L; { const int q = nwg / NXCD, r = nwg % NXCD, xcd = wgid % NXCD, off = wgid / NXCD; wgid = (xcd < r ? xcd * (q + 1) : r * (q + 1) + (xcd - r) * q) + off; }
;         const int nig = wgm * nN, gid = wgid / nig, fm = gid * wgm, gsz = (nM - fm) < wgm ? (nM - fm) : wgm;
;         u.pm = fm + ((wgid % nig) % gsz); u.pn = (wgid % nig) / gsz; return true;
;     }
; template <class Epi, class Sched, bool ALIGN_EPI = false, bool SP2 = false>
; __device__ __forceinline__ void gemm_phase(PG8_LAS unsigned char* lds, const Gemm g, const Sched& S, const Epi& E) {
;     ...
;     const char* cA = (const char*)g.A + (size_t)cur.pm * tstepA + (size_t)cur.pn * pnA; const char* cB = (const char*)g.Bt + (size_t)cur.pn * tstepB;
;     S.a_ready(cur);
;     if constexpr (SP2) {
;         PG8_STAGE(PG8_SB(0, 0), cB, voffB); PG8_STAGE(PG8_SB(0, 1), cB + hstepB, voffB); PG8_STAGE(PG8_SA(0, 0), cA, voffA); PG8_STAGE(PG8_SA(0, 1), cA + hstepA, voffA);
;         if (wr == 1) PG8_BAR;
;         PG8_WAIT_V(2); PG8_BAR;
;         PG8_STAGE(PG8_SB(1, 0), cB + kstep, voffB); PG8_STAGE(PG8_SA(1, 0), cA + kstep, voffA); PG8_STAGE(PG8_SB(1, 1), cB + hstepB + kstep, voffB);
;         PG8_WAIT_V(6); PG8_BAR;
;     } else {
;         PG8_STAGE(PG8_SB(0, 0), cB, voffB); PG8_STAGE(PG8_SA(0, 0), cA, voffA); PG8_STAGE(PG8_SB(0, 1), cB + hstepB, voffB); PG8_STAGE(PG8_SA(0, 1), cA + hstepA, voffA);
;         if (wr == 1) PG8_BAR;
;         PG8_WAIT_V(4); PG8_BAR;
;         PG8_STAGE(PG8_SB(1, 0), cB + kstep, voffB); PG8_STAGE(PG8_SA(1, 0), cA + kstep, voffA); PG8_STAGE(PG8_SB(1, 1), cB + hstepB + kstep, voffB);
.LBB0_825:
	v_bfe_i32 v4, v2, 27, 1
	v_lshlrev_b32_e32 v3, 4, v2
	v_lshrrev_b32_e32 v4, 22, v4
	v_add_u32_e32 v4, v3, v4
	v_and_b32_e32 v4, 0xfffffc00, v4
	v_sub_u32_e32 v4, v3, v4
	v_lshrrev_b32_e32 v5, 4, v4
	v_ashrrev_i32_e32 v1, 31, v2
	v_bitop3_b32 v4, v5, v4, 32 bitop3:0x6c
	s_mul_i32 s3, s52, 0x5b00000
	v_lshrrev_b32_e32 v1, 26, v1
	s_waitcnt vmcnt(6)
	v_ashrrev_i32_e32 v6, 31, v4
	s_mul_hi_i32 s2, s52, 0x5b00000
	s_waitcnt lgkmcnt(0)
	s_add_u32 s3, s4, s3
	v_add_u32_e32 v1, v2, v1
	v_lshrrev_b32_e32 v6, 26, v6
	s_addc_u32 s7, s5, s2
	v_ashrrev_i32_e32 v1, 6, v1
	v_add_u32_e32 v6, v4, v6
	s_add_u32 s2, s4, 0x1ec00000
	v_lshlrev_b32_e32 v5, 3, v1
	v_ashrrev_i32_e32 v7, 6, v6
	v_and_b32_e32 v6, 0xc0, v6
	s_addc_u32 s19, s5, 0
	v_and_b32_e32 v5, -16, v5
	v_lshlrev_b32_e32 v1, 5, v1
	v_sub_u32_e32 v4, v4, v6
	v_mov_b32_e32 v8, 1
	s_add_u32 s22, s3, 0x4400000
	v_add_u32_e32 v5, v7, v5
	v_and_b32_e32 v1, 32, v1
	v_ashrrev_i16_sdwa v4, v8, sext(v4) dst_sel:DWORD dst_unused:UNUSED_PAD src0_sel:DWORD src1_sel:BYTE_0
	s_addc_u32 s24, s7, 0
	v_add_u32_sdwa v4, v1, sext(v4) dst_sel:DWORD dst_unused:UNUSED_PAD src0_sel:DWORD src1_sel:WORD_0
	v_lshlrev_b32_e32 v1, 1, v5
	v_lshrrev_b32_e32 v6, 2, v5
	v_and_b32_e32 v7, 3, v7
	s_mov_b32 s7, 0x7fffe0
	v_and_b32_e32 v1, 24, v1
	v_and_b32_e32 v6, 4, v6
	v_and_or_b32 v7, v5, s7, v7
	v_or3_b32 v6, v7, v6, v1
	s_movk_i32 s3, 0x1600
	v_mul_lo_u32 v1, v5, s3
	v_mul_u32_u24_e32 v5, 0x1600, v6
	v_add_u32_e32 v3, 0x2000, v3
	v_add_lshl_u32 v1, v4, v1, 1
	v_add_lshl_u32 v132, v5, v4, 1
	v_ashrrev_i32_e32 v4, 31, v3
	v_lshrrev_b32_e32 v4, 22, v4
	v_add_u32_e32 v4, v3, v4
	v_ashrrev_i32_e32 v4, 10, v4
	v_mul_i32_i24_e32 v5, 0x400, v4
	v_sub_u32_e32 v3, v3, v5
	v_lshrrev_b32_e32 v5, 4, v3
	v_bitop3_b32 v3, v5, v3, 32 bitop3:0x6c
	v_ashrrev_i32_e32 v6, 31, v3
	v_lshrrev_b32_e32 v6, 26, v6
	v_lshlrev_b32_e32 v5, 3, v4
	v_add_u32_e32 v6, v3, v6
	v_and_b32_e32 v5, -16, v5
	v_ashrrev_i32_e32 v7, 6, v6
	v_add_u32_e32 v5, v7, v5
	v_and_b32_e32 v7, 3, v7
	s_add_i32 s6, s8, s6
	v_and_or_b32 v7, v5, s7, v7
	s_ashr_i32 s7, s6, 31
	s_lshr_b32 s7, s7, 27
	s_add_i32 s7, s6, s7
	s_ashr_i32 s8, s7, 5
	s_and_b32 s7, s7, 0xffe0
	s_sub_i32 s6, s6, s7
	s_bfe_i32 s7, s6, 0x80000
	s_bfe_u32 s7, s7, 0x2000d
	s_add_i32 s7, s6, s7
	s_bfe_i32 s9, s7, 0x80000
	s_and_b32 s7, s7, 0xfc
	v_and_b32_e32 v6, 0xc0, v6
	s_sub_i32 s6, s6, s7
	v_lshlrev_b32_e32 v4, 5, v4
	v_sub_u32_e32 v3, v3, v6
	s_lshl_b32 s8, s8, 2
	s_sext_i32_i16 s9, s9
	s_sext_i32_i8 s6, s6
	s_ashr_i32 s13, s12, 6
	v_and_b32_e32 v4, 32, v4
	v_ashrrev_i16_sdwa v3, v8, sext(v3) dst_sel:DWORD dst_unused:UNUSED_PAD src0_sel:DWORD src1_sel:BYTE_0
	s_add_i32 s71, s8, s6
	s_xor_b32 s71, s71, 15
	s_ashr_i32 s8, s9, 2
	v_add_u32_sdwa v3, v4, sext(v3) dst_sel:DWORD dst_unused:UNUSED_PAD src0_sel:DWORD src1_sel:WORD_0
	v_lshlrev_b32_e32 v4, 1, v5
	v_lshrrev_b32_e32 v6, 2, v5
	v_mul_lo_u32 v5, v5, s3
	s_ashr_i32 s16, s12, 8
	s_lshl_b32 s3, s13, 10
	s_lshr_b32 s10, s9, 2
	s_mul_hi_i32 s9, s8, 0x2c0000
	s_mul_i32 s8, s8, 0x2c0000
	s_add_u32 s54, s22, s8
	s_addc_u32 s55, s24, s9
	s_add_i32 s28, s3, 0
	v_and_b32_e32 v4, 24, v4
	v_and_b32_e32 v6, 4, v6
	s_mul_i32 s7, s71, 0x2c0000
	s_add_i32 s29, s28, 0x10000
	s_add_i32 s30, s28, 0x12000
	v_or3_b32 v4, v7, v6, v4
	s_mul_hi_i32 s6, s71, 0x2c0000
	s_add_u32 s56, s2, s7
	v_mul_u32_u24_e32 v4, 0x1600, v4
	s_mov_b32 m0, s29
	s_nop 0
	global_load_lds_dwordx4 v132, s[54:55]
	s_addc_u32 s57, s19, s6
	v_add_lshl_u32 v134, v4, v3, 1
	s_mov_b32 m0, s30
	s_nop 0
	global_load_lds_dwordx4 v134, s[54:55]
	s_add_u32 s6, s54, 0x160000
	s_addc_u32 s7, s55, 0
	s_add_i32 s33, s28, 0x14000
	s_mov_b32 m0, s33
	s_nop 0
	global_load_lds_dwordx4 v132, s[6:7]
	s_add_i32 s43, s28, 0x16000
	s_mov_b32 m0, s43
	s_nop 0
	global_load_lds_dwordx4 v134, s[6:7]
	s_add_i32 s50, s28, 0x2000
	s_mov_b32 m0, s28
	s_nop 0
	global_load_lds_dwordx4 v1, s[56:57]
	v_add_lshl_u32 v133, v3, v5, 1
	s_mov_b32 m0, s50
	s_nop 0
	global_load_lds_dwordx4 v133, s[56:57]
	s_add_u32 s8, s56, 0x160000
	s_addc_u32 s9, s57, 0
	s_add_i32 s51, s28, 0x4000
	s_mov_b32 m0, s51
	s_nop 0
	global_load_lds_dwordx4 v1, s[8:9]
	s_mov_b32 s80, s52
	s_add_i32 s52, s28, 0x6000
	s_mov_b32 m0, s52
	s_nop 0
	global_load_lds_dwordx4 v133, s[8:9]
	s_cmp_eq_u32 s16, 1
	s_cselect_b64 s[8:9], -1, 0
	s_cmp_lg_u32 s16, 1
	s_cbranch_scc1 .LBB0_827
	s_barrier

;     __host__ __device__ bool next(int i, Unit& u) const {
;         const long L = (long)i * G + c; if (L >= nwg) return false;
;         int wgid = (int)L; { const int q = nwg / NXCD, r = nwg % NXCD, xcd = wgid % NXCD, off = wgid / NXCD; wgid = (xcd < r ? xcd * (q + 1) : r * (q + 1) + (xcd - r) * q) + off; }
;         const int nig = wgm * nN, gid = wgid / nig, fm = gid * wgm, gsz = (nM - fm) < wgm ? (nM - fm) : wgm;
;         u.pm = fm + ((wgid % nig) % gsz); u.pn = (wgid % nig) / gsz; return true;
;     }
.LBB0_835:
	s_ashr_i32 s3, s16, 3
	s_add_i32 s3, s18, s3
	s_ashr_i32 s4, s3, 31
	s_lshr_b32 s4, s4, 27
	s_add_i32 s4, s3, s4
	s_ashr_i32 s5, s4, 5
	s_lshl_b32 s5, s5, 2
	s_sub_i32 s16, 0x80, s5
	s_min_i32 s16, s16, 4
	s_abs_i32 s17, s16
	v_cvt_f32_u32_e32 v2, s17
	s_sub_i32 s58, 0, s17
	s_andn2_b32 s4, s4, 31
	s_sub_i32 s3, s3, s4
	v_rcp_iflag_f32_e32 v2, v2
	s_abs_i32 s4, s3
	s_xor_b32 s18, s3, s16
	s_ashr_i32 s18, s18, 31
	v_mul_f32_e32 v2, 0x4f7ffffe, v2
	v_cvt_u32_f32_e32 v2, v2
	s_nop 0
	v_readfirstlane_b32 s59, v2
	s_mul_i32 s58, s58, s59
	s_mul_hi_u32 s58, s59, s58
	s_add_i32 s59, s59, s58
	s_mul_hi_u32 s58, s4, s59
	s_mul_i32 s59, s58, s17
	s_sub_i32 s4, s4, s59
	s_add_i32 s60, s58, 1
	s_sub_i32 s59, s4, s17
	s_cmp_ge_u32 s4, s17
	s_cselect_b32 s58, s60, s58
	s_cselect_b32 s4, s59, s4
	s_add_i32 s59, s58, 1
	s_cmp_ge_u32 s4, s17
	s_cselect_b32 s4, s59, s58
	s_xor_b32 s4, s4, s18
	s_sub_i32 s69, s4, s18
	s_mul_i32 s4, s69, s16
	s_sub_i32 s3, s3, s4
	s_add_i32 s70, s5, s3
	s_xor_b32 s70, s70, 15
